# P2 k4-loop stream hook polls IB_STS vmcnt and skips consume/issue while the chunk is still in flight
# baseline (speedup 1.0000x reference)
; #define LAS __attribute__((address_space(3)))
; __device__ __forceinline__ unsigned pk2(float lo, float hi) { return f2bf(lo) | (f2bf(hi) << 16); }
; __device__ __forceinline__ void chunk_ab(const f32x4 (&v)[16], const LAS bf16_t* wl, int lane, f32x4& A, f32x4& B) {
;     A = (f32x4){0.f, 0.f, 0.f, 0.f}; B = A;
;     const LAS bf16_t* wlane = wl + 4 * lane; asm volatile("" : "+v"(wlane));
; #pragma unroll
;     for (int j = 0; j < 16; ++j) { const u32x2 wa = *(const LAS u32x2*)(wlane + j * 256), wb = *(const LAS u32x2*)(wlane + (16 + j) * 256);
;         A += v[j] * (f32x4){bflo(wa.x), bfhi(wa.x), bflo(wa.y), bfhi(wa.y)}; B += v[j] * (f32x4){bflo(wb.x), bfhi(wb.x), bflo(wb.y), bfhi(wb.y)}; }
; __device__ __forceinline__ void cs_consume(const Prm& P, CStream& S, const LAS bf16_t* wlb, int NGW) {
;     if (S.pend) {
;         int lane; asm volatile("v_mbcnt_lo_u32_b32 %0, -1, 0\n\tv_mbcnt_hi_u32_b32 %0, -1, %0" : "=v"(lane));
;         const int b = S.tk >> 7, p = S.tk & 127;
;         bf16_t* dst = (bf16_t*)(P.ws + WS_KCS) + (size_t)b * 1024 * 256;
;         if (S.pend == 1) {
;             f32x4 A0, B0; chunk_ab(S.v, wlb, lane, A0, B0);
;             if (S.i >= 1) { const int n = 8 * p + S.i - 1; if (n < 1023) { const f32x4 s = S.Aprev + B0; st8_pl(dst + (size_t)n * 256 + 4 * lane, pk2(s[0], s[1]), pk2(s[2], s[3])); } }
;             S.Aprev = A0;
.LBB0_1262:
	v_mov_b32_e32 v241, v235
	v_mov_b32_e32 v240, v234
	v_mov_b32_e32 v15, v233
	v_mov_b32_e32 v14, v236
	v_mov_b32_e32 v235, v205
	v_mov_b32_e32 v234, v204
	v_mov_b32_e32 v233, v207
	s_cmp_ge_i32 s12, s10
	v_mov_b32_e32 v236, v206
	s_cbranch_scc1 .LBB0_1272
	s_cmp_eq_u32 s38, 0
	s_cbranch_scc1 .LBB0_1276
	s_cmp_lg_u32 s38, 1
	s_cbranch_scc1 .Lpc_go
	s_getreg_b32 s8, hwreg(HW_REG_IB_STS)
	s_and_b32 s8, s8, 0xc0000f
	s_cmp_lg_u32 s8, 0
	s_cbranch_scc1 .LBB0_1281
.Lpc_go:
	s_ashr_i32 s8, s62, 7
	s_ashr_i32 s9, s8, 31
	s_and_b32 s14, s62, 0x7f
	s_lshl_b64 s[8:9], s[8:9], 19
	s_add_u32 s8, s63, s8
	s_addc_u32 s9, s64, s9
	s_cmp_lg_u32 s38, 1
	v_mbcnt_lo_u32_b32 v1, -1, 0
	v_mbcnt_hi_u32_b32 v1, -1, v1
	s_cbranch_scc1 .LBB0_1273
	v_lshl_add_u32 v6, v1, 3, s68
	ds_read2st64_b64 v[2:5], v6 offset1:1
	ds_read2st64_b64 v[8:11], v6 offset0:2 offset1:3
	s_cmp_lt_i32 s60, 1
	s_waitcnt lgkmcnt(1)
	v_lshlrev_b32_e32 v12, 16, v2
	v_and_b32_e32 v13, 0xffff0000, v2
	v_lshlrev_b32_e32 v2, 16, v3
	v_and_b32_e32 v3, 0xffff0000, v3
	s_waitcnt vmcnt(15)
	v_pk_fma_f32 v[12:13], v[64:65], v[12:13], 0 op_sel_hi:[1,1,0]
	v_pk_fma_f32 v[2:3], v[66:67], v[2:3], 0 op_sel_hi:[1,1,0]
	v_lshlrev_b32_e32 v48, 16, v4
	v_and_b32_e32 v49, 0xffff0000, v4
	v_lshlrev_b32_e32 v4, 16, v5
	v_and_b32_e32 v5, 0xffff0000, v5
	s_waitcnt vmcnt(14)
	v_pk_fma_f32 v[2:3], v[70:71], v[4:5], v[2:3]
	v_pk_fma_f32 v[4:5], v[68:69], v[48:49], v[12:13]
	s_waitcnt lgkmcnt(0)
	v_lshlrev_b32_e32 v12, 16, v8
	v_and_b32_e32 v13, 0xffff0000, v8
	v_lshlrev_b32_e32 v8, 16, v9
	v_and_b32_e32 v9, 0xffff0000, v9
	s_waitcnt vmcnt(13)
	v_pk_fma_f32 v[12:13], v[72:73], v[12:13], v[4:5]
	v_pk_fma_f32 v[8:9], v[74:75], v[8:9], v[2:3]
	ds_read2st64_b64 v[2:5], v6 offset0:4 offset1:5
	v_lshlrev_b32_e32 v48, 16, v10
	v_and_b32_e32 v49, 0xffff0000, v10
	v_lshlrev_b32_e32 v10, 16, v11
	v_and_b32_e32 v11, 0xffff0000, v11
	s_waitcnt vmcnt(12)
	v_pk_fma_f32 v[50:51], v[78:79], v[10:11], v[8:9]
	ds_read2st64_b64 v[8:11], v6 offset0:6 offset1:7
	v_pk_fma_f32 v[12:13], v[76:77], v[48:49], v[12:13]
	s_waitcnt lgkmcnt(1)
	v_lshlrev_b32_e32 v48, 16, v2
	v_and_b32_e32 v49, 0xffff0000, v2
	v_lshlrev_b32_e32 v2, 16, v3
	v_and_b32_e32 v3, 0xffff0000, v3
	s_waitcnt vmcnt(11)
	v_pk_fma_f32 v[12:13], v[88:89], v[48:49], v[12:13]
	v_pk_fma_f32 v[2:3], v[90:91], v[2:3], v[50:51]
	v_lshlrev_b32_e32 v48, 16, v4
	v_and_b32_e32 v49, 0xffff0000, v4
	v_lshlrev_b32_e32 v4, 16, v5
	v_and_b32_e32 v5, 0xffff0000, v5
	s_waitcnt vmcnt(10)
	v_pk_fma_f32 v[2:3], v[82:83], v[4:5], v[2:3]
	v_pk_fma_f32 v[4:5], v[80:81], v[48:49], v[12:13]
	s_waitcnt lgkmcnt(0)
	v_lshlrev_b32_e32 v12, 16, v8
	v_and_b32_e32 v13, 0xffff0000, v8
	v_lshlrev_b32_e32 v8, 16, v9
	v_and_b32_e32 v9, 0xffff0000, v9
	s_waitcnt vmcnt(9)
	v_pk_fma_f32 v[12:13], v[84:85], v[12:13], v[4:5]
	v_pk_fma_f32 v[8:9], v[86:87], v[8:9], v[2:3]
	ds_read2st64_b64 v[2:5], v6 offset0:8 offset1:9
	v_lshlrev_b32_e32 v48, 16, v10
	v_and_b32_e32 v49, 0xffff0000, v10
	v_lshlrev_b32_e32 v10, 16, v11
	v_and_b32_e32 v11, 0xffff0000, v11
	s_waitcnt vmcnt(8)
	v_pk_fma_f32 v[50:51], v[94:95], v[10:11], v[8:9]
	ds_read2st64_b64 v[8:11], v6 offset0:10 offset1:11
	v_pk_fma_f32 v[12:13], v[92:93], v[48:49], v[12:13]
	s_waitcnt lgkmcnt(1)
	v_lshlrev_b32_e32 v48, 16, v2
	v_and_b32_e32 v49, 0xffff0000, v2
	v_lshlrev_b32_e32 v2, 16, v3
	v_and_b32_e32 v3, 0xffff0000, v3
	s_waitcnt vmcnt(7)
	v_pk_fma_f32 v[12:13], v[96:97], v[48:49], v[12:13]
	v_pk_fma_f32 v[2:3], v[98:99], v[2:3], v[50:51]
	v_lshlrev_b32_e32 v48, 16, v4
	v_and_b32_e32 v49, 0xffff0000, v4
	v_lshlrev_b32_e32 v4, 16, v5
	v_and_b32_e32 v5, 0xffff0000, v5
	s_waitcnt vmcnt(6)
	v_pk_fma_f32 v[2:3], v[102:103], v[4:5], v[2:3]
	v_pk_fma_f32 v[4:5], v[100:101], v[48:49], v[12:13]
	s_waitcnt lgkmcnt(0)
	v_lshlrev_b32_e32 v12, 16, v8
	v_and_b32_e32 v13, 0xffff0000, v8
	v_lshlrev_b32_e32 v8, 16, v9
	v_and_b32_e32 v9, 0xffff0000, v9
	s_waitcnt vmcnt(5)
	v_pk_fma_f32 v[12:13], v[104:105], v[12:13], v[4:5]
	v_pk_fma_f32 v[8:9], v[106:107], v[8:9], v[2:3]
	ds_read2st64_b64 v[2:5], v6 offset0:12 offset1:13
	v_lshlrev_b32_e32 v48, 16, v10
	v_and_b32_e32 v49, 0xffff0000, v10
	v_lshlrev_b32_e32 v10, 16, v11
	v_and_b32_e32 v11, 0xffff0000, v11
	s_waitcnt vmcnt(4)
	v_pk_fma_f32 v[50:51], v[110:111], v[10:11], v[8:9]
	ds_read2st64_b64 v[8:11], v6 offset0:14 offset1:15
	v_pk_fma_f32 v[12:13], v[108:109], v[48:49], v[12:13]
	s_waitcnt lgkmcnt(1)
	v_lshlrev_b32_e32 v48, 16, v2
	v_and_b32_e32 v49, 0xffff0000, v2
	v_lshlrev_b32_e32 v2, 16, v3
	v_and_b32_e32 v3, 0xffff0000, v3
	s_waitcnt vmcnt(3)
	v_pk_fma_f32 v[12:13], v[112:113], v[48:49], v[12:13]
	v_pk_fma_f32 v[2:3], v[114:115], v[2:3], v[50:51]
	v_lshlrev_b32_e32 v48, 16, v4
	v_and_b32_e32 v49, 0xffff0000, v4
	v_lshlrev_b32_e32 v4, 16, v5
	v_and_b32_e32 v5, 0xffff0000, v5
	s_waitcnt vmcnt(2)
	v_pk_fma_f32 v[2:3], v[118:119], v[4:5], v[2:3]
	v_pk_fma_f32 v[4:5], v[116:117], v[48:49], v[12:13]
	s_waitcnt lgkmcnt(0)
	v_lshlrev_b32_e32 v12, 16, v8
	v_and_b32_e32 v13, 0xffff0000, v8
	v_lshlrev_b32_e32 v8, 16, v9
	v_and_b32_e32 v9, 0xffff0000, v9
	s_waitcnt vmcnt(1)
	v_pk_fma_f32 v[12:13], v[120:121], v[12:13], v[4:5]
	v_pk_fma_f32 v[2:3], v[122:123], v[8:9], v[2:3]
	v_lshlrev_b32_e32 v8, 16, v10
	v_and_b32_e32 v9, 0xffff0000, v10
	v_lshlrev_b32_e32 v4, 16, v11
	v_and_b32_e32 v5, 0xffff0000, v11
	s_waitcnt vmcnt(0)
	v_pk_fma_f32 v[4:5], v[126:127], v[4:5], v[2:3]
	v_pk_fma_f32 v[2:3], v[124:125], v[8:9], v[12:13]
	s_cbranch_scc1 .LBB0_1268
; #define LAS __attribute__((address_space(3)))
; __device__ __forceinline__ unsigned pk2(float lo, float hi) { return f2bf(lo) | (f2bf(hi) << 16); }
; __device__ __forceinline__ void chunk_ab(const f32x4 (&v)[16], const LAS bf16_t* wl, int lane, f32x4& A, f32x4& B) {
;     A = (f32x4){0.f, 0.f, 0.f, 0.f}; B = A;
;     const LAS bf16_t* wlane = wl + 4 * lane; asm volatile("" : "+v"(wlane));
; #pragma unroll
;     for (int j = 0; j < 16; ++j) { const u32x2 wa = *(const LAS u32x2*)(wlane + j * 256), wb = *(const LAS u32x2*)(wlane + (16 + j) * 256);
;         A += v[j] * (f32x4){bflo(wa.x), bfhi(wa.x), bflo(wa.y), bfhi(wa.y)}; B += v[j] * (f32x4){bflo(wb.x), bfhi(wb.x), bflo(wb.y), bfhi(wb.y)}; }
; }
; __device__ __forceinline__ void cs_consume(const Prm& P, CStream& S, const LAS bf16_t* wlb, int NGW) {
;     ...
;         if (S.pend == 1) {
;             f32x4 A0, B0; chunk_ab(S.v, wlb, lane, A0, B0);
;             if (S.i >= 1) { const int n = 8 * p + S.i - 1; if (n < 1023) { const f32x4 s = S.Aprev + B0; st8_pl(dst + (size_t)n * 256 + 4 * lane, pk2(s[0], s[1]), pk2(s[2], s[3])); } }
;             S.Aprev = A0;
	s_lshl_b32 s15, s14, 3
	s_add_i32 s15, s15, s60
	s_cmpk_gt_u32 s15, 0x3ff
	s_cbranch_scc1 .LBB0_1268
	ds_read2st64_b64 v[8:11], v6 offset0:16 offset1:17
	ds_read2st64_b64 v[48:51], v6 offset0:18 offset1:19
	ds_read2st64_b64 v[52:55], v6 offset0:20 offset1:21
	ds_read2st64_b64 v[56:59], v6 offset0:22 offset1:23
	ds_read2st64_b64 v[60:63], v6 offset0:24 offset1:25
	ds_read2st64_b64 v[180:183], v6 offset0:26 offset1:27
	ds_read2st64_b64 v[184:187], v6 offset0:28 offset1:29
	ds_read2st64_b64 v[204:207], v6 offset0:30 offset1:31
	s_waitcnt lgkmcnt(7)
	v_lshlrev_b32_e32 v6, 16, v8
	v_and_b32_e32 v7, 0xffff0000, v8
	v_lshlrev_b32_e32 v8, 16, v9
	v_and_b32_e32 v9, 0xffff0000, v9
	v_pk_fma_f32 v[8:9], v[66:67], v[8:9], 0 op_sel_hi:[1,1,0]
	v_pk_fma_f32 v[6:7], v[64:65], v[6:7], 0 op_sel_hi:[1,1,0]
	v_lshlrev_b32_e32 v12, 16, v10
	v_and_b32_e32 v13, 0xffff0000, v10
	v_lshlrev_b32_e32 v10, 16, v11
	v_and_b32_e32 v11, 0xffff0000, v11
	v_pk_fma_f32 v[6:7], v[68:69], v[12:13], v[6:7]
	v_pk_fma_f32 v[8:9], v[70:71], v[10:11], v[8:9]
	s_waitcnt lgkmcnt(6)
	v_lshlrev_b32_e32 v10, 16, v48
	v_and_b32_e32 v11, 0xffff0000, v48
	v_pk_fma_f32 v[6:7], v[72:73], v[10:11], v[6:7]
	v_lshlrev_b32_e32 v10, 16, v50
	v_and_b32_e32 v11, 0xffff0000, v50
	v_lshlrev_b32_e32 v12, 16, v49
	v_and_b32_e32 v13, 0xffff0000, v49
	v_pk_fma_f32 v[6:7], v[76:77], v[10:11], v[6:7]
	s_waitcnt lgkmcnt(5)
	v_lshlrev_b32_e32 v10, 16, v52
	v_and_b32_e32 v11, 0xffff0000, v52
	v_pk_fma_f32 v[8:9], v[74:75], v[12:13], v[8:9]
	v_lshlrev_b32_e32 v12, 16, v51
	v_and_b32_e32 v13, 0xffff0000, v51
	v_pk_fma_f32 v[6:7], v[88:89], v[10:11], v[6:7]
	v_lshlrev_b32_e32 v10, 16, v54
	v_and_b32_e32 v11, 0xffff0000, v54
	v_pk_fma_f32 v[8:9], v[78:79], v[12:13], v[8:9]
	v_lshlrev_b32_e32 v12, 16, v53
	v_and_b32_e32 v13, 0xffff0000, v53
	v_pk_fma_f32 v[6:7], v[80:81], v[10:11], v[6:7]
	s_waitcnt lgkmcnt(4)
	v_lshlrev_b32_e32 v10, 16, v56
	v_and_b32_e32 v11, 0xffff0000, v56
	v_pk_fma_f32 v[8:9], v[90:91], v[12:13], v[8:9]
	v_lshlrev_b32_e32 v12, 16, v55
	v_and_b32_e32 v13, 0xffff0000, v55
	v_pk_fma_f32 v[6:7], v[84:85], v[10:11], v[6:7]
	v_lshlrev_b32_e32 v10, 16, v58
	v_and_b32_e32 v11, 0xffff0000, v58
	v_pk_fma_f32 v[8:9], v[82:83], v[12:13], v[8:9]
	v_lshlrev_b32_e32 v12, 16, v57
	v_and_b32_e32 v13, 0xffff0000, v57
	v_pk_fma_f32 v[6:7], v[92:93], v[10:11], v[6:7]
	s_waitcnt lgkmcnt(3)
	v_lshlrev_b32_e32 v10, 16, v60
	v_and_b32_e32 v11, 0xffff0000, v60
	v_pk_fma_f32 v[8:9], v[86:87], v[12:13], v[8:9]
	v_lshlrev_b32_e32 v12, 16, v59
	v_and_b32_e32 v13, 0xffff0000, v59
	v_pk_fma_f32 v[6:7], v[96:97], v[10:11], v[6:7]
	v_lshlrev_b32_e32 v10, 16, v62
	v_and_b32_e32 v11, 0xffff0000, v62
	v_pk_fma_f32 v[8:9], v[94:95], v[12:13], v[8:9]
	v_lshlrev_b32_e32 v12, 16, v61
	v_and_b32_e32 v13, 0xffff0000, v61
	v_pk_fma_f32 v[6:7], v[100:101], v[10:11], v[6:7]
	s_waitcnt lgkmcnt(2)
	v_lshlrev_b32_e32 v10, 16, v180
	v_and_b32_e32 v11, 0xffff0000, v180
	v_pk_fma_f32 v[8:9], v[98:99], v[12:13], v[8:9]
	v_lshlrev_b32_e32 v12, 16, v63
	v_and_b32_e32 v13, 0xffff0000, v63
	v_pk_fma_f32 v[6:7], v[104:105], v[10:11], v[6:7]
	v_lshlrev_b32_e32 v10, 16, v182
	v_and_b32_e32 v11, 0xffff0000, v182
	v_pk_fma_f32 v[8:9], v[102:103], v[12:13], v[8:9]
	v_lshlrev_b32_e32 v12, 16, v181
	v_and_b32_e32 v13, 0xffff0000, v181
	v_pk_fma_f32 v[6:7], v[108:109], v[10:11], v[6:7]
	s_waitcnt lgkmcnt(1)
	v_lshlrev_b32_e32 v10, 16, v184
	v_and_b32_e32 v11, 0xffff0000, v184
	v_pk_fma_f32 v[8:9], v[106:107], v[12:13], v[8:9]
	v_lshlrev_b32_e32 v12, 16, v183
	v_and_b32_e32 v13, 0xffff0000, v183
	v_pk_fma_f32 v[6:7], v[112:113], v[10:11], v[6:7]
	v_lshlrev_b32_e32 v10, 16, v186
	v_and_b32_e32 v11, 0xffff0000, v186
	v_pk_fma_f32 v[8:9], v[110:111], v[12:13], v[8:9]
	v_lshlrev_b32_e32 v12, 16, v185
	v_and_b32_e32 v13, 0xffff0000, v185
	v_pk_fma_f32 v[6:7], v[116:117], v[10:11], v[6:7]
	s_waitcnt lgkmcnt(0)
	v_lshlrev_b32_e32 v10, 16, v204
	v_and_b32_e32 v11, 0xffff0000, v204
	v_pk_fma_f32 v[8:9], v[114:115], v[12:13], v[8:9]
	v_lshlrev_b32_e32 v12, 16, v187
	v_and_b32_e32 v13, 0xffff0000, v187
	v_pk_fma_f32 v[6:7], v[120:121], v[10:11], v[6:7]
	v_lshlrev_b32_e32 v10, 16, v206
	v_and_b32_e32 v11, 0xffff0000, v206
	v_pk_fma_f32 v[8:9], v[118:119], v[12:13], v[8:9]
	v_lshlrev_b32_e32 v12, 16, v205
	v_and_b32_e32 v13, 0xffff0000, v205
	v_pk_fma_f32 v[6:7], v[124:125], v[10:11], v[6:7]
	v_pk_fma_f32 v[8:9], v[122:123], v[12:13], v[8:9]
	v_lshlrev_b32_e32 v12, 16, v207
	v_and_b32_e32 v13, 0xffff0000, v207
	v_pk_add_f32 v[6:7], v[128:129], v[6:7]
	v_pk_fma_f32 v[8:9], v[126:127], v[12:13], v[8:9]
	s_add_i32 s38, s15, -1
	v_pk_add_f32 v[8:9], v[130:131], v[8:9]
	s_lshl_b64 s[16:17], s[38:39], 9
	v_cvt_pk_bf16_f32 v6, v6, v7
	s_add_u32 s16, s8, s16
	v_lshlrev_b32_e32 v10, 2, v1
	s_addc_u32 s17, s9, s17
	v_ashrrev_i32_e32 v11, 31, v10
	v_lshl_add_u64 v[10:11], v[10:11], 1, s[16:17]
	v_cvt_pk_bf16_f32 v7, v8, v9
	global_store_dwordx2 v[10:11], v[6:7], off
